# UP epilogue: previous-block rows read from LDS only by the lanes that use them (fr == 0) + last block skips unused exchange writes
# speedup vs baseline: 1.0034x; 1.0034x over previous
.Lnepia_nohalo:
	s_or_b64 exec, exec, s[8:9]
	s_waitcnt lgkmcnt(0)
	s_barrier
	s_cmp_eq_u32 s50, 0
	s_cbranch_scc1 .Lnepia_z0
	v_cmp_eq_u32_e32 vcc, 0, v224
	s_and_saveexec_b64 s[8:9], vcc
	ds_read_b128 v[118:121], v227 offset:512
	ds_read_b128 v[122:125], v227 offset:1536
	s_or_b64 exec, exec, s[8:9]
	s_branch .Lnepia_j0

.Lnepia_j0:
	s_waitcnt lgkmcnt(0)
	v_cmp_eq_u32_e32 vcc, 0, v224
	s_and_saveexec_b64 s[8:9], vcc
	ds_read_b128 v[162:165], v227 offset:4608
	ds_read_b128 v[166:169], v227 offset:5632
	s_or_b64 exec, exec, s[8:9]
	v_mov_b32_dpp v118, v78 row_shr:1 row_mask:0xf bank_mask:0xf
	v_mov_b32_dpp v122, v138 row_shr:1 row_mask:0xf bank_mask:0xf
	v_mov_b32_dpp v119, v79 row_shr:1 row_mask:0xf bank_mask:0xf
	v_mov_b32_dpp v123, v139 row_shr:1 row_mask:0xf bank_mask:0xf
	v_mov_b32_dpp v120, v80 row_shr:1 row_mask:0xf bank_mask:0xf
	v_mov_b32_dpp v124, v140 row_shr:1 row_mask:0xf bank_mask:0xf
	v_mov_b32_dpp v121, v81 row_shr:1 row_mask:0xf bank_mask:0xf
	v_mov_b32_dpp v125, v141 row_shr:1 row_mask:0xf bank_mask:0xf
	v_pk_fma_f32 v[138:139], v[202:203], v[138:139], v[206:207]
	v_pk_fma_f32 v[140:141], v[204:205], v[140:141], v[208:209]
	v_pk_fma_f32 v[138:139], v[198:199], v[78:79], v[138:139]
	v_pk_fma_f32 v[140:141], v[200:201], v[80:81], v[140:141]
	v_pk_fma_f32 v[138:139], v[194:195], v[130:131], v[138:139]
	v_pk_fma_f32 v[140:141], v[196:197], v[132:133], v[140:141]
	v_pk_fma_f32 v[78:79], v[202:203], v[78:79], v[206:207]
	v_pk_fma_f32 v[80:81], v[204:205], v[80:81], v[208:209]
	v_pk_fma_f32 v[78:79], v[198:199], v[130:131], v[78:79]
	v_pk_fma_f32 v[80:81], v[200:201], v[132:133], v[80:81]
	v_pk_fma_f32 v[78:79], v[194:195], v[134:135], v[78:79]
	v_pk_fma_f32 v[80:81], v[196:197], v[136:137], v[80:81]
	v_pk_fma_f32 v[130:131], v[202:203], v[130:131], v[206:207]
	v_pk_fma_f32 v[132:133], v[204:205], v[132:133], v[208:209]
	v_pk_fma_f32 v[130:131], v[198:199], v[134:135], v[130:131]
	v_pk_fma_f32 v[132:133], v[200:201], v[136:137], v[132:133]
	v_pk_fma_f32 v[130:131], v[194:195], v[122:123], v[130:131]
	v_pk_fma_f32 v[132:133], v[196:197], v[124:125], v[132:133]
	v_pk_fma_f32 v[134:135], v[202:203], v[134:135], v[206:207]
	v_pk_fma_f32 v[136:137], v[204:205], v[136:137], v[208:209]
	v_pk_fma_f32 v[134:135], v[198:199], v[122:123], v[134:135]
	v_pk_fma_f32 v[136:137], v[200:201], v[124:125], v[136:137]
	v_pk_fma_f32 v[134:135], v[194:195], v[118:119], v[134:135]
	v_pk_fma_f32 v[136:137], v[196:197], v[120:121], v[136:137]
	s_cmp_lg_u32 s50, 0
	s_cbranch_scc1 .Lnepia_np0
	v_cmp_eq_u32_e32 vcc, 0, v224
	s_and_saveexec_b64 s[8:9], vcc
	s_add_u32 s48, s88, 0x2d00000
	s_addc_u32 s49, s89, 0
	global_store_dwordx4 v229, v[134:137], s[48:49] offset:0
	global_store_dwordx4 v231, v[130:133], s[48:49] offset:0
	s_or_b64 exec, exec, s[8:9]
	s_nop 1
.Lnepia_np0:
	s_waitcnt lgkmcnt(0)
	ds_read_b128 v[146:149], v226 offset:0
	ds_read_b128 v[150:153], v226 offset:1024
	ds_read_b128 v[154:157], v226 offset:2048
	ds_read_b128 v[158:161], v226 offset:3072
	s_cmp_eq_u32 s50, 0
	s_cbranch_scc1 .Lnepia_z2
	v_cmp_eq_u32_e32 vcc, 0, v224
	s_and_saveexec_b64 s[8:9], vcc
	ds_read_b128 v[118:121], v227 offset:0
	ds_read_b128 v[122:125], v227 offset:1024
	s_or_b64 exec, exec, s[8:9]
	s_branch .Lnepia_j2

.Lnepia_j2:
	v_mov_b32_dpp v162, v102 row_shr:1 row_mask:0xf bank_mask:0xf
	v_mov_b32_dpp v166, v126 row_shr:1 row_mask:0xf bank_mask:0xf
	v_mov_b32_dpp v163, v103 row_shr:1 row_mask:0xf bank_mask:0xf
	v_mov_b32_dpp v167, v127 row_shr:1 row_mask:0xf bank_mask:0xf
	v_mov_b32_dpp v164, v104 row_shr:1 row_mask:0xf bank_mask:0xf
	v_mov_b32_dpp v168, v128 row_shr:1 row_mask:0xf bank_mask:0xf
	v_mov_b32_dpp v165, v105 row_shr:1 row_mask:0xf bank_mask:0xf
	v_mov_b32_dpp v169, v129 row_shr:1 row_mask:0xf bank_mask:0xf
	v_pk_fma_f32 v[126:127], v[202:203], v[126:127], v[206:207]
	v_pk_fma_f32 v[128:129], v[204:205], v[128:129], v[208:209]
	v_pk_fma_f32 v[126:127], v[198:199], v[102:103], v[126:127]
	v_pk_fma_f32 v[128:129], v[200:201], v[104:105], v[128:129]
	v_pk_fma_f32 v[126:127], v[194:195], v[106:107], v[126:127]
	v_pk_fma_f32 v[128:129], v[196:197], v[108:109], v[128:129]
	v_pk_fma_f32 v[102:103], v[202:203], v[102:103], v[206:207]
	v_pk_fma_f32 v[104:105], v[204:205], v[104:105], v[208:209]
	v_pk_fma_f32 v[102:103], v[198:199], v[106:107], v[102:103]
	v_pk_fma_f32 v[104:105], v[200:201], v[108:109], v[104:105]
	v_pk_fma_f32 v[102:103], v[194:195], v[110:111], v[102:103]
	v_pk_fma_f32 v[104:105], v[196:197], v[112:113], v[104:105]
	v_pk_fma_f32 v[106:107], v[202:203], v[106:107], v[206:207]
	v_pk_fma_f32 v[108:109], v[204:205], v[108:109], v[208:209]
	v_pk_fma_f32 v[106:107], v[198:199], v[110:111], v[106:107]
	v_pk_fma_f32 v[108:109], v[200:201], v[112:113], v[108:109]
	v_pk_fma_f32 v[106:107], v[194:195], v[166:167], v[106:107]
	v_pk_fma_f32 v[108:109], v[196:197], v[168:169], v[108:109]
	v_pk_fma_f32 v[110:111], v[202:203], v[110:111], v[206:207]
	v_pk_fma_f32 v[112:113], v[204:205], v[112:113], v[208:209]
	v_pk_fma_f32 v[110:111], v[198:199], v[166:167], v[110:111]
	v_pk_fma_f32 v[112:113], v[200:201], v[168:169], v[112:113]
	v_pk_fma_f32 v[110:111], v[194:195], v[162:163], v[110:111]
	v_pk_fma_f32 v[112:113], v[196:197], v[164:165], v[112:113]
	s_waitcnt lgkmcnt(0)
	v_cmp_eq_u32_e32 vcc, 0, v224
	s_and_saveexec_b64 s[8:9], vcc
	ds_read_b128 v[162:165], v227 offset:4096
	ds_read_b128 v[166:169], v227 offset:5120
	s_or_b64 exec, exec, s[8:9]
	v_mov_b32_dpp v118, v46 row_shr:1 row_mask:0xf bank_mask:0xf
	v_mov_b32_dpp v122, v142 row_shr:1 row_mask:0xf bank_mask:0xf
	v_mov_b32_dpp v119, v47 row_shr:1 row_mask:0xf bank_mask:0xf
	v_mov_b32_dpp v123, v143 row_shr:1 row_mask:0xf bank_mask:0xf
	v_mov_b32_dpp v120, v48 row_shr:1 row_mask:0xf bank_mask:0xf
	v_mov_b32_dpp v124, v144 row_shr:1 row_mask:0xf bank_mask:0xf
	v_mov_b32_dpp v121, v49 row_shr:1 row_mask:0xf bank_mask:0xf
	v_mov_b32_dpp v125, v145 row_shr:1 row_mask:0xf bank_mask:0xf
	v_pk_fma_f32 v[142:143], v[154:155], v[142:143], v[158:159]
	v_pk_fma_f32 v[144:145], v[156:157], v[144:145], v[160:161]
	v_pk_fma_f32 v[142:143], v[150:151], v[46:47], v[142:143]
	v_pk_fma_f32 v[144:145], v[152:153], v[48:49], v[144:145]
	v_pk_fma_f32 v[142:143], v[146:147], v[50:51], v[142:143]
	v_pk_fma_f32 v[144:145], v[148:149], v[52:53], v[144:145]
	v_pk_fma_f32 v[46:47], v[154:155], v[46:47], v[158:159]
	v_pk_fma_f32 v[48:49], v[156:157], v[48:49], v[160:161]
	v_pk_fma_f32 v[46:47], v[150:151], v[50:51], v[46:47]
	v_pk_fma_f32 v[48:49], v[152:153], v[52:53], v[48:49]
	v_pk_fma_f32 v[46:47], v[146:147], v[62:63], v[46:47]
	v_pk_fma_f32 v[48:49], v[148:149], v[64:65], v[48:49]
	v_pk_fma_f32 v[50:51], v[154:155], v[50:51], v[158:159]
	v_pk_fma_f32 v[52:53], v[156:157], v[52:53], v[160:161]
	v_pk_fma_f32 v[50:51], v[150:151], v[62:63], v[50:51]
	v_pk_fma_f32 v[52:53], v[152:153], v[64:65], v[52:53]
	v_pk_fma_f32 v[50:51], v[146:147], v[122:123], v[50:51]
	v_pk_fma_f32 v[52:53], v[148:149], v[124:125], v[52:53]
	v_pk_fma_f32 v[62:63], v[154:155], v[62:63], v[158:159]
	v_pk_fma_f32 v[64:65], v[156:157], v[64:65], v[160:161]
	v_pk_fma_f32 v[62:63], v[150:151], v[122:123], v[62:63]
	v_pk_fma_f32 v[64:65], v[152:153], v[124:125], v[64:65]
	v_pk_fma_f32 v[62:63], v[146:147], v[118:119], v[62:63]
	v_pk_fma_f32 v[64:65], v[148:149], v[120:121], v[64:65]
	s_cmp_lg_u32 s50, 0
	s_cbranch_scc1 .Lnepia_np2
	v_cmp_eq_u32_e32 vcc, 0, v224
	s_and_saveexec_b64 s[8:9], vcc
	s_add_u32 s48, s88, 0x2d00000
	s_addc_u32 s49, s89, 0
	global_store_dwordx4 v228, v[62:65], s[48:49] offset:0
	global_store_dwordx4 v230, v[50:53], s[48:49] offset:0
	s_or_b64 exec, exec, s[8:9]
	s_nop 1
.Lnepia_np2:
	v_pk_mul_f32 v[30:31], v[62:63], s[100:101]
	v_pk_mul_f32 v[32:33], v[64:65], s[100:101]
	v_pk_mul_f32 v[54:55], v[50:51], s[100:101]
	v_pk_mul_f32 v[56:57], v[52:53], s[100:101]
	v_exp_f32_e32 v30, v30
	v_exp_f32_e32 v31, v31
	v_exp_f32_e32 v32, v32
	v_exp_f32_e32 v33, v33
	v_exp_f32_e32 v54, v54
	v_exp_f32_e32 v55, v55
	v_exp_f32_e32 v56, v56
	v_exp_f32_e32 v57, v57
	v_pk_add_f32 v[30:31], v[30:31], s[98:99]
	v_pk_add_f32 v[32:33], v[32:33], s[98:99]
	v_pk_add_f32 v[54:55], v[54:55], s[98:99]
	v_pk_add_f32 v[56:57], v[56:57], s[98:99]
	v_rcp_f32_e32 v30, v30
	v_rcp_f32_e32 v31, v31
	v_rcp_f32_e32 v32, v32
	v_rcp_f32_e32 v33, v33
	v_rcp_f32_e32 v54, v54
	v_rcp_f32_e32 v55, v55
	v_rcp_f32_e32 v56, v56
	v_rcp_f32_e32 v57, v57
	v_pk_mul_f32 v[62:63], v[62:63], v[134:135]
	v_pk_mul_f32 v[64:65], v[64:65], v[136:137]
	v_pk_mul_f32 v[50:51], v[50:51], v[130:131]
	v_pk_mul_f32 v[52:53], v[52:53], v[132:133]
	v_pk_mul_f32 v[62:63], v[62:63], v[30:31]
	v_pk_mul_f32 v[64:65], v[64:65], v[32:33]
	v_pk_mul_f32 v[50:51], v[50:51], v[54:55]
	v_pk_mul_f32 v[52:53], v[52:53], v[56:57]
	v_pk_mul_f32 v[30:31], v[46:47], s[100:101]
	v_pk_mul_f32 v[32:33], v[48:49], s[100:101]
	v_pk_mul_f32 v[54:55], v[142:143], s[100:101]
	v_pk_mul_f32 v[56:57], v[144:145], s[100:101]
	v_exp_f32_e32 v30, v30
	v_exp_f32_e32 v31, v31
	v_exp_f32_e32 v32, v32
	v_exp_f32_e32 v33, v33
	v_exp_f32_e32 v54, v54
	v_exp_f32_e32 v55, v55
	v_exp_f32_e32 v56, v56
	v_exp_f32_e32 v57, v57
	v_pk_add_f32 v[30:31], v[30:31], s[98:99]
	v_pk_add_f32 v[32:33], v[32:33], s[98:99]
	v_pk_add_f32 v[54:55], v[54:55], s[98:99]
	v_pk_add_f32 v[56:57], v[56:57], s[98:99]
	v_rcp_f32_e32 v30, v30
	v_rcp_f32_e32 v31, v31
	v_rcp_f32_e32 v32, v32
	v_rcp_f32_e32 v33, v33
	v_rcp_f32_e32 v54, v54
	v_rcp_f32_e32 v55, v55
	v_rcp_f32_e32 v56, v56
	v_rcp_f32_e32 v57, v57
	v_pk_mul_f32 v[46:47], v[46:47], v[78:79]
	v_pk_mul_f32 v[48:49], v[48:49], v[80:81]
	v_pk_mul_f32 v[142:143], v[142:143], v[138:139]
	v_pk_mul_f32 v[144:145], v[144:145], v[140:141]
	v_pk_mul_f32 v[46:47], v[46:47], v[30:31]
	v_pk_mul_f32 v[48:49], v[48:49], v[32:33]
	v_pk_mul_f32 v[142:143], v[142:143], v[54:55]
	v_pk_mul_f32 v[144:145], v[144:145], v[56:57]
	s_waitcnt lgkmcnt(0)
	ds_read_b128 v[194:197], v226 offset:528
	ds_read_b128 v[198:201], v226 offset:1552
	ds_read_b128 v[202:205], v226 offset:2576
	ds_read_b128 v[206:209], v226 offset:3600
	s_cmp_eq_u32 s50, 0
	s_cbranch_scc1 .Lnepia_z4
	v_cmp_eq_u32_e32 vcc, 0, v224
	s_and_saveexec_b64 s[8:9], vcc
	ds_read_b128 v[118:121], v227 offset:528
	ds_read_b128 v[122:125], v227 offset:1552
	s_or_b64 exec, exec, s[8:9]
	s_branch .Lnepia_j4

.Lnepia_j4:
	v_mov_b32_dpp v162, v86 row_shr:1 row_mask:0xf bank_mask:0xf
	v_mov_b32_dpp v166, v114 row_shr:1 row_mask:0xf bank_mask:0xf
	v_mov_b32_dpp v163, v87 row_shr:1 row_mask:0xf bank_mask:0xf
	v_mov_b32_dpp v167, v115 row_shr:1 row_mask:0xf bank_mask:0xf
	v_mov_b32_dpp v164, v88 row_shr:1 row_mask:0xf bank_mask:0xf
	v_mov_b32_dpp v168, v116 row_shr:1 row_mask:0xf bank_mask:0xf
	v_mov_b32_dpp v165, v89 row_shr:1 row_mask:0xf bank_mask:0xf
	v_mov_b32_dpp v169, v117 row_shr:1 row_mask:0xf bank_mask:0xf
	v_pk_fma_f32 v[114:115], v[154:155], v[114:115], v[158:159]
	v_pk_fma_f32 v[116:117], v[156:157], v[116:117], v[160:161]
	v_pk_fma_f32 v[114:115], v[150:151], v[86:87], v[114:115]
	v_pk_fma_f32 v[116:117], v[152:153], v[88:89], v[116:117]
	v_pk_fma_f32 v[114:115], v[146:147], v[90:91], v[114:115]
	v_pk_fma_f32 v[116:117], v[148:149], v[92:93], v[116:117]
	v_pk_fma_f32 v[86:87], v[154:155], v[86:87], v[158:159]
	v_pk_fma_f32 v[88:89], v[156:157], v[88:89], v[160:161]
	v_pk_fma_f32 v[86:87], v[150:151], v[90:91], v[86:87]
	v_pk_fma_f32 v[88:89], v[152:153], v[92:93], v[88:89]
	v_pk_fma_f32 v[86:87], v[146:147], v[94:95], v[86:87]
	v_pk_fma_f32 v[88:89], v[148:149], v[96:97], v[88:89]
	v_pk_fma_f32 v[90:91], v[154:155], v[90:91], v[158:159]
	v_pk_fma_f32 v[92:93], v[156:157], v[92:93], v[160:161]
	v_pk_fma_f32 v[90:91], v[150:151], v[94:95], v[90:91]
	v_pk_fma_f32 v[92:93], v[152:153], v[96:97], v[92:93]
	v_pk_fma_f32 v[90:91], v[146:147], v[166:167], v[90:91]
	v_pk_fma_f32 v[92:93], v[148:149], v[168:169], v[92:93]
	v_pk_fma_f32 v[94:95], v[154:155], v[94:95], v[158:159]
	v_pk_fma_f32 v[96:97], v[156:157], v[96:97], v[160:161]
	v_pk_fma_f32 v[94:95], v[150:151], v[166:167], v[94:95]
	v_pk_fma_f32 v[96:97], v[152:153], v[168:169], v[96:97]
	v_pk_fma_f32 v[94:95], v[146:147], v[162:163], v[94:95]
	v_pk_fma_f32 v[96:97], v[148:149], v[164:165], v[96:97]
	v_pk_mul_f32 v[30:31], v[94:95], s[100:101]
	v_pk_mul_f32 v[32:33], v[96:97], s[100:101]
	v_pk_mul_f32 v[54:55], v[90:91], s[100:101]
	v_pk_mul_f32 v[56:57], v[92:93], s[100:101]
	v_exp_f32_e32 v30, v30
	v_exp_f32_e32 v31, v31
	v_exp_f32_e32 v32, v32
	v_exp_f32_e32 v33, v33
	v_exp_f32_e32 v54, v54
	v_exp_f32_e32 v55, v55
	v_exp_f32_e32 v56, v56
	v_exp_f32_e32 v57, v57
	v_pk_add_f32 v[30:31], v[30:31], s[98:99]
	v_pk_add_f32 v[32:33], v[32:33], s[98:99]
	v_pk_add_f32 v[54:55], v[54:55], s[98:99]
	v_pk_add_f32 v[56:57], v[56:57], s[98:99]
	v_rcp_f32_e32 v30, v30
	v_rcp_f32_e32 v31, v31
	v_rcp_f32_e32 v32, v32
	v_rcp_f32_e32 v33, v33
	v_rcp_f32_e32 v54, v54
	v_rcp_f32_e32 v55, v55
	v_rcp_f32_e32 v56, v56
	v_rcp_f32_e32 v57, v57
	v_pk_mul_f32 v[94:95], v[94:95], v[110:111]
	v_pk_mul_f32 v[96:97], v[96:97], v[112:113]
	v_pk_mul_f32 v[90:91], v[90:91], v[106:107]
	v_pk_mul_f32 v[92:93], v[92:93], v[108:109]
	v_pk_mul_f32 v[94:95], v[94:95], v[30:31]
	v_pk_mul_f32 v[96:97], v[96:97], v[32:33]
	v_pk_mul_f32 v[90:91], v[90:91], v[54:55]
	v_pk_mul_f32 v[92:93], v[92:93], v[56:57]
	v_pk_mul_f32 v[30:31], v[86:87], s[100:101]
	v_pk_mul_f32 v[32:33], v[88:89], s[100:101]
	v_pk_mul_f32 v[54:55], v[114:115], s[100:101]
	v_pk_mul_f32 v[56:57], v[116:117], s[100:101]
	v_exp_f32_e32 v30, v30
	v_exp_f32_e32 v31, v31
	v_exp_f32_e32 v32, v32
	v_exp_f32_e32 v33, v33
	v_exp_f32_e32 v54, v54
	v_exp_f32_e32 v55, v55
	v_exp_f32_e32 v56, v56
	v_exp_f32_e32 v57, v57
	v_pk_add_f32 v[30:31], v[30:31], s[98:99]
	v_pk_add_f32 v[32:33], v[32:33], s[98:99]
	v_pk_add_f32 v[54:55], v[54:55], s[98:99]
	v_pk_add_f32 v[56:57], v[56:57], s[98:99]
	v_rcp_f32_e32 v30, v30
	v_rcp_f32_e32 v31, v31
	v_rcp_f32_e32 v32, v32
	v_rcp_f32_e32 v33, v33
	v_rcp_f32_e32 v54, v54
	v_rcp_f32_e32 v55, v55
	v_rcp_f32_e32 v56, v56
	v_rcp_f32_e32 v57, v57
	v_pk_mul_f32 v[86:87], v[86:87], v[102:103]
	v_pk_mul_f32 v[88:89], v[88:89], v[104:105]
	v_pk_mul_f32 v[114:115], v[114:115], v[126:127]
	v_pk_mul_f32 v[116:117], v[116:117], v[128:129]
	v_pk_mul_f32 v[86:87], v[86:87], v[30:31]
	v_pk_mul_f32 v[88:89], v[88:89], v[32:33]
	v_pk_mul_f32 v[114:115], v[114:115], v[54:55]
	v_pk_mul_f32 v[116:117], v[116:117], v[56:57]
	s_waitcnt lgkmcnt(0)
	v_cmp_eq_u32_e32 vcc, 0, v224
	s_and_saveexec_b64 s[8:9], vcc
	ds_read_b128 v[162:165], v227 offset:4624
	ds_read_b128 v[166:169], v227 offset:5648
	s_or_b64 exec, exec, s[8:9]
	v_mov_b32_dpp v118, v66 row_shr:1 row_mask:0xf bank_mask:0xf
	v_mov_b32_dpp v122, v98 row_shr:1 row_mask:0xf bank_mask:0xf
	v_mov_b32_dpp v119, v67 row_shr:1 row_mask:0xf bank_mask:0xf
	v_mov_b32_dpp v123, v99 row_shr:1 row_mask:0xf bank_mask:0xf
	v_mov_b32_dpp v120, v68 row_shr:1 row_mask:0xf bank_mask:0xf
	v_mov_b32_dpp v124, v100 row_shr:1 row_mask:0xf bank_mask:0xf
	v_mov_b32_dpp v121, v69 row_shr:1 row_mask:0xf bank_mask:0xf
	v_mov_b32_dpp v125, v101 row_shr:1 row_mask:0xf bank_mask:0xf
	v_pk_fma_f32 v[98:99], v[202:203], v[98:99], v[206:207]
	v_pk_fma_f32 v[100:101], v[204:205], v[100:101], v[208:209]
	v_pk_fma_f32 v[98:99], v[198:199], v[66:67], v[98:99]
	v_pk_fma_f32 v[100:101], v[200:201], v[68:69], v[100:101]
	v_pk_fma_f32 v[98:99], v[194:195], v[70:71], v[98:99]
	v_pk_fma_f32 v[100:101], v[196:197], v[72:73], v[100:101]
	v_pk_fma_f32 v[66:67], v[202:203], v[66:67], v[206:207]
	v_pk_fma_f32 v[68:69], v[204:205], v[68:69], v[208:209]
	v_pk_fma_f32 v[66:67], v[198:199], v[70:71], v[66:67]
	v_pk_fma_f32 v[68:69], v[200:201], v[72:73], v[68:69]
	v_pk_fma_f32 v[66:67], v[194:195], v[74:75], v[66:67]
	v_pk_fma_f32 v[68:69], v[196:197], v[76:77], v[68:69]
	v_pk_fma_f32 v[70:71], v[202:203], v[70:71], v[206:207]
	v_pk_fma_f32 v[72:73], v[204:205], v[72:73], v[208:209]
	v_pk_fma_f32 v[70:71], v[198:199], v[74:75], v[70:71]
	v_pk_fma_f32 v[72:73], v[200:201], v[76:77], v[72:73]
	v_pk_fma_f32 v[70:71], v[194:195], v[122:123], v[70:71]
	v_pk_fma_f32 v[72:73], v[196:197], v[124:125], v[72:73]
	v_pk_fma_f32 v[74:75], v[202:203], v[74:75], v[206:207]
	v_pk_fma_f32 v[76:77], v[204:205], v[76:77], v[208:209]
	v_pk_fma_f32 v[74:75], v[198:199], v[122:123], v[74:75]
	v_pk_fma_f32 v[76:77], v[200:201], v[124:125], v[76:77]
	v_pk_fma_f32 v[74:75], v[194:195], v[118:119], v[74:75]
	v_pk_fma_f32 v[76:77], v[196:197], v[120:121], v[76:77]
	s_cmp_lg_u32 s50, 0
	s_cbranch_scc1 .Lnepia_np4
	v_cmp_eq_u32_e32 vcc, 0, v224
	s_and_saveexec_b64 s[8:9], vcc
	s_add_u32 s48, s88, 0x2d00000
	s_addc_u32 s49, s89, 0
	global_store_dwordx4 v229, v[74:77], s[48:49] offset:16
	global_store_dwordx4 v231, v[70:73], s[48:49] offset:16
	s_or_b64 exec, exec, s[8:9]
	s_nop 1
.Lnepia_np4:
	s_waitcnt lgkmcnt(0)
	ds_read_b128 v[146:149], v226 offset:16
	ds_read_b128 v[150:153], v226 offset:1040
	ds_read_b128 v[154:157], v226 offset:2064
	ds_read_b128 v[158:161], v226 offset:3088
	s_cmp_eq_u32 s50, 0
	s_cbranch_scc1 .Lnepia_z6
	v_cmp_eq_u32_e32 vcc, 0, v224
	s_and_saveexec_b64 s[8:9], vcc
	ds_read_b128 v[118:121], v227 offset:16
	ds_read_b128 v[122:125], v227 offset:1040
	s_or_b64 exec, exec, s[8:9]
	s_branch .Lnepia_j6

.Lnepia_j6:
	v_mov_b32_dpp v162, v14 row_shr:1 row_mask:0xf bank_mask:0xf
	v_mov_b32_dpp v166, v58 row_shr:1 row_mask:0xf bank_mask:0xf
	v_mov_b32_dpp v163, v15 row_shr:1 row_mask:0xf bank_mask:0xf
	v_mov_b32_dpp v167, v59 row_shr:1 row_mask:0xf bank_mask:0xf
	v_mov_b32_dpp v164, v16 row_shr:1 row_mask:0xf bank_mask:0xf
	v_mov_b32_dpp v168, v60 row_shr:1 row_mask:0xf bank_mask:0xf
	v_mov_b32_dpp v165, v17 row_shr:1 row_mask:0xf bank_mask:0xf
	v_mov_b32_dpp v169, v61 row_shr:1 row_mask:0xf bank_mask:0xf
	v_pk_fma_f32 v[58:59], v[202:203], v[58:59], v[206:207]
	v_pk_fma_f32 v[60:61], v[204:205], v[60:61], v[208:209]
	v_pk_fma_f32 v[58:59], v[198:199], v[14:15], v[58:59]
	v_pk_fma_f32 v[60:61], v[200:201], v[16:17], v[60:61]
	v_pk_fma_f32 v[58:59], v[194:195], v[18:19], v[58:59]
	v_pk_fma_f32 v[60:61], v[196:197], v[20:21], v[60:61]
	v_pk_fma_f32 v[14:15], v[202:203], v[14:15], v[206:207]
	v_pk_fma_f32 v[16:17], v[204:205], v[16:17], v[208:209]
	v_pk_fma_f32 v[14:15], v[198:199], v[18:19], v[14:15]
	v_pk_fma_f32 v[16:17], v[200:201], v[20:21], v[16:17]
	v_pk_fma_f32 v[14:15], v[194:195], v[22:23], v[14:15]
	v_pk_fma_f32 v[16:17], v[196:197], v[24:25], v[16:17]
	v_pk_fma_f32 v[18:19], v[202:203], v[18:19], v[206:207]
	v_pk_fma_f32 v[20:21], v[204:205], v[20:21], v[208:209]
	v_pk_fma_f32 v[18:19], v[198:199], v[22:23], v[18:19]
	v_pk_fma_f32 v[20:21], v[200:201], v[24:25], v[20:21]
	v_pk_fma_f32 v[18:19], v[194:195], v[166:167], v[18:19]
	v_pk_fma_f32 v[20:21], v[196:197], v[168:169], v[20:21]
	v_pk_fma_f32 v[22:23], v[202:203], v[22:23], v[206:207]
	v_pk_fma_f32 v[24:25], v[204:205], v[24:25], v[208:209]
	v_pk_fma_f32 v[22:23], v[198:199], v[166:167], v[22:23]
	v_pk_fma_f32 v[24:25], v[200:201], v[168:169], v[24:25]
	v_pk_fma_f32 v[22:23], v[194:195], v[162:163], v[22:23]
	v_pk_fma_f32 v[24:25], v[196:197], v[164:165], v[24:25]
	s_waitcnt lgkmcnt(0)
	v_cmp_eq_u32_e32 vcc, 0, v224
	s_and_saveexec_b64 s[8:9], vcc
	ds_read_b128 v[162:165], v227 offset:4112
	ds_read_b128 v[166:169], v227 offset:5136
	s_or_b64 exec, exec, s[8:9]
	v_mov_b32_dpp v118, v34 row_shr:1 row_mask:0xf bank_mask:0xf
	v_mov_b32_dpp v122, v82 row_shr:1 row_mask:0xf bank_mask:0xf
	v_mov_b32_dpp v119, v35 row_shr:1 row_mask:0xf bank_mask:0xf
	v_mov_b32_dpp v123, v83 row_shr:1 row_mask:0xf bank_mask:0xf
	v_mov_b32_dpp v120, v36 row_shr:1 row_mask:0xf bank_mask:0xf
	v_mov_b32_dpp v124, v84 row_shr:1 row_mask:0xf bank_mask:0xf
	v_mov_b32_dpp v121, v37 row_shr:1 row_mask:0xf bank_mask:0xf
	v_mov_b32_dpp v125, v85 row_shr:1 row_mask:0xf bank_mask:0xf
	v_pk_fma_f32 v[82:83], v[154:155], v[82:83], v[158:159]
	v_pk_fma_f32 v[84:85], v[156:157], v[84:85], v[160:161]
	v_pk_fma_f32 v[82:83], v[150:151], v[34:35], v[82:83]
	v_pk_fma_f32 v[84:85], v[152:153], v[36:37], v[84:85]
	v_pk_fma_f32 v[82:83], v[146:147], v[38:39], v[82:83]
	v_pk_fma_f32 v[84:85], v[148:149], v[40:41], v[84:85]
	v_pk_fma_f32 v[34:35], v[154:155], v[34:35], v[158:159]
	v_pk_fma_f32 v[36:37], v[156:157], v[36:37], v[160:161]
	v_pk_fma_f32 v[34:35], v[150:151], v[38:39], v[34:35]
	v_pk_fma_f32 v[36:37], v[152:153], v[40:41], v[36:37]
	v_pk_fma_f32 v[34:35], v[146:147], v[42:43], v[34:35]
	v_pk_fma_f32 v[36:37], v[148:149], v[44:45], v[36:37]
	v_pk_fma_f32 v[38:39], v[154:155], v[38:39], v[158:159]
	v_pk_fma_f32 v[40:41], v[156:157], v[40:41], v[160:161]
	v_pk_fma_f32 v[38:39], v[150:151], v[42:43], v[38:39]
	v_pk_fma_f32 v[40:41], v[152:153], v[44:45], v[40:41]
	v_pk_fma_f32 v[38:39], v[146:147], v[122:123], v[38:39]
	v_pk_fma_f32 v[40:41], v[148:149], v[124:125], v[40:41]
	v_pk_fma_f32 v[42:43], v[154:155], v[42:43], v[158:159]
	v_pk_fma_f32 v[44:45], v[156:157], v[44:45], v[160:161]
	v_pk_fma_f32 v[42:43], v[150:151], v[122:123], v[42:43]
	v_pk_fma_f32 v[44:45], v[152:153], v[124:125], v[44:45]
	v_pk_fma_f32 v[42:43], v[146:147], v[118:119], v[42:43]
	v_pk_fma_f32 v[44:45], v[148:149], v[120:121], v[44:45]
	s_cmp_lg_u32 s50, 0
	s_cbranch_scc1 .Lnepia_np6
	v_cmp_eq_u32_e32 vcc, 0, v224
	s_and_saveexec_b64 s[8:9], vcc
	s_add_u32 s48, s88, 0x2d00000
	s_addc_u32 s49, s89, 0
	global_store_dwordx4 v228, v[42:45], s[48:49] offset:16
	global_store_dwordx4 v230, v[38:41], s[48:49] offset:16
	s_or_b64 exec, exec, s[8:9]
	s_nop 1

.Lnepib_nohalo:
	s_or_b64 exec, exec, s[8:9]
	s_waitcnt lgkmcnt(0)
	s_barrier
	s_cmp_eq_u32 s54, 0
	s_cbranch_scc1 .Lnepib_z0
	v_cmp_eq_u32_e32 vcc, 0, v224
	s_and_saveexec_b64 s[8:9], vcc
	ds_read_b128 v[118:121], v227 offset:512
	ds_read_b128 v[122:125], v227 offset:1536
	s_or_b64 exec, exec, s[8:9]
	s_branch .Lnepib_j0

.Lnepib_j0:
	s_waitcnt lgkmcnt(0)
	v_cmp_eq_u32_e32 vcc, 0, v224
	s_and_saveexec_b64 s[8:9], vcc
	ds_read_b128 v[162:165], v227 offset:4608
	ds_read_b128 v[166:169], v227 offset:5632
	s_or_b64 exec, exec, s[8:9]
	v_mov_b32_dpp v118, v78 row_shr:1 row_mask:0xf bank_mask:0xf
	v_mov_b32_dpp v122, v138 row_shr:1 row_mask:0xf bank_mask:0xf
	v_mov_b32_dpp v119, v79 row_shr:1 row_mask:0xf bank_mask:0xf
	v_mov_b32_dpp v123, v139 row_shr:1 row_mask:0xf bank_mask:0xf
	v_mov_b32_dpp v120, v80 row_shr:1 row_mask:0xf bank_mask:0xf
	v_mov_b32_dpp v124, v140 row_shr:1 row_mask:0xf bank_mask:0xf
	v_mov_b32_dpp v121, v81 row_shr:1 row_mask:0xf bank_mask:0xf
	v_mov_b32_dpp v125, v141 row_shr:1 row_mask:0xf bank_mask:0xf
	v_pk_fma_f32 v[138:139], v[204:205], v[138:139], v[208:209]
	v_pk_fma_f32 v[140:141], v[206:207], v[140:141], v[210:211]
	v_pk_fma_f32 v[138:139], v[200:201], v[78:79], v[138:139]
	v_pk_fma_f32 v[140:141], v[202:203], v[80:81], v[140:141]
	v_pk_fma_f32 v[138:139], v[196:197], v[130:131], v[138:139]
	v_pk_fma_f32 v[140:141], v[198:199], v[132:133], v[140:141]
	v_pk_fma_f32 v[78:79], v[204:205], v[78:79], v[208:209]
	v_pk_fma_f32 v[80:81], v[206:207], v[80:81], v[210:211]
	v_pk_fma_f32 v[78:79], v[200:201], v[130:131], v[78:79]
	v_pk_fma_f32 v[80:81], v[202:203], v[132:133], v[80:81]
	v_pk_fma_f32 v[78:79], v[196:197], v[134:135], v[78:79]
	v_pk_fma_f32 v[80:81], v[198:199], v[136:137], v[80:81]
	v_pk_fma_f32 v[130:131], v[204:205], v[130:131], v[208:209]
	v_pk_fma_f32 v[132:133], v[206:207], v[132:133], v[210:211]
	v_pk_fma_f32 v[130:131], v[200:201], v[134:135], v[130:131]
	v_pk_fma_f32 v[132:133], v[202:203], v[136:137], v[132:133]
	v_pk_fma_f32 v[130:131], v[196:197], v[122:123], v[130:131]
	v_pk_fma_f32 v[132:133], v[198:199], v[124:125], v[132:133]
	v_pk_fma_f32 v[134:135], v[204:205], v[134:135], v[208:209]
	v_pk_fma_f32 v[136:137], v[206:207], v[136:137], v[210:211]
	v_pk_fma_f32 v[134:135], v[200:201], v[122:123], v[134:135]
	v_pk_fma_f32 v[136:137], v[202:203], v[124:125], v[136:137]
	v_pk_fma_f32 v[134:135], v[196:197], v[118:119], v[134:135]
	v_pk_fma_f32 v[136:137], v[198:199], v[120:121], v[136:137]
	s_cmp_lg_u32 s54, 0
	s_cbranch_scc1 .Lnepib_np0
	v_cmp_eq_u32_e32 vcc, 0, v224
	s_and_saveexec_b64 s[8:9], vcc
	s_add_u32 s52, s88, 0x2d00000
	s_addc_u32 s53, s89, 0
	global_store_dwordx4 v229, v[134:137], s[52:53] offset:0
	global_store_dwordx4 v231, v[130:133], s[52:53] offset:0
	s_or_b64 exec, exec, s[8:9]
	s_nop 1
.Lnepib_np0:
	s_waitcnt lgkmcnt(0)
	ds_read_b128 v[146:149], v226 offset:0
	ds_read_b128 v[150:153], v226 offset:1024
	ds_read_b128 v[154:157], v226 offset:2048
	ds_read_b128 v[158:161], v226 offset:3072
	s_cmp_eq_u32 s54, 0
	s_cbranch_scc1 .Lnepib_z2
	v_cmp_eq_u32_e32 vcc, 0, v224
	s_and_saveexec_b64 s[8:9], vcc
	ds_read_b128 v[118:121], v227 offset:0
	ds_read_b128 v[122:125], v227 offset:1024
	s_or_b64 exec, exec, s[8:9]
	s_branch .Lnepib_j2

.Lnepib_j2:
	v_mov_b32_dpp v162, v102 row_shr:1 row_mask:0xf bank_mask:0xf
	v_mov_b32_dpp v166, v126 row_shr:1 row_mask:0xf bank_mask:0xf
	v_mov_b32_dpp v163, v103 row_shr:1 row_mask:0xf bank_mask:0xf
	v_mov_b32_dpp v167, v127 row_shr:1 row_mask:0xf bank_mask:0xf
	v_mov_b32_dpp v164, v104 row_shr:1 row_mask:0xf bank_mask:0xf
	v_mov_b32_dpp v168, v128 row_shr:1 row_mask:0xf bank_mask:0xf
	v_mov_b32_dpp v165, v105 row_shr:1 row_mask:0xf bank_mask:0xf
	v_mov_b32_dpp v169, v129 row_shr:1 row_mask:0xf bank_mask:0xf
	v_pk_fma_f32 v[126:127], v[204:205], v[126:127], v[208:209]
	v_pk_fma_f32 v[128:129], v[206:207], v[128:129], v[210:211]
	v_pk_fma_f32 v[126:127], v[200:201], v[102:103], v[126:127]
	v_pk_fma_f32 v[128:129], v[202:203], v[104:105], v[128:129]
	v_pk_fma_f32 v[126:127], v[196:197], v[106:107], v[126:127]
	v_pk_fma_f32 v[128:129], v[198:199], v[108:109], v[128:129]
	v_pk_fma_f32 v[102:103], v[204:205], v[102:103], v[208:209]
	v_pk_fma_f32 v[104:105], v[206:207], v[104:105], v[210:211]
	v_pk_fma_f32 v[102:103], v[200:201], v[106:107], v[102:103]
	v_pk_fma_f32 v[104:105], v[202:203], v[108:109], v[104:105]
	v_pk_fma_f32 v[102:103], v[196:197], v[110:111], v[102:103]
	v_pk_fma_f32 v[104:105], v[198:199], v[112:113], v[104:105]
	v_pk_fma_f32 v[106:107], v[204:205], v[106:107], v[208:209]
	v_pk_fma_f32 v[108:109], v[206:207], v[108:109], v[210:211]
	v_pk_fma_f32 v[106:107], v[200:201], v[110:111], v[106:107]
	v_pk_fma_f32 v[108:109], v[202:203], v[112:113], v[108:109]
	v_pk_fma_f32 v[106:107], v[196:197], v[166:167], v[106:107]
	v_pk_fma_f32 v[108:109], v[198:199], v[168:169], v[108:109]
	v_pk_fma_f32 v[110:111], v[204:205], v[110:111], v[208:209]
	v_pk_fma_f32 v[112:113], v[206:207], v[112:113], v[210:211]
	v_pk_fma_f32 v[110:111], v[200:201], v[166:167], v[110:111]
	v_pk_fma_f32 v[112:113], v[202:203], v[168:169], v[112:113]
	v_pk_fma_f32 v[110:111], v[196:197], v[162:163], v[110:111]
	v_pk_fma_f32 v[112:113], v[198:199], v[164:165], v[112:113]
	s_waitcnt lgkmcnt(0)
	v_cmp_eq_u32_e32 vcc, 0, v224
	s_and_saveexec_b64 s[8:9], vcc
	ds_read_b128 v[162:165], v227 offset:4096
	ds_read_b128 v[166:169], v227 offset:5120
	s_or_b64 exec, exec, s[8:9]
	v_mov_b32_dpp v118, v46 row_shr:1 row_mask:0xf bank_mask:0xf
	v_mov_b32_dpp v122, v142 row_shr:1 row_mask:0xf bank_mask:0xf
	v_mov_b32_dpp v119, v47 row_shr:1 row_mask:0xf bank_mask:0xf
	v_mov_b32_dpp v123, v143 row_shr:1 row_mask:0xf bank_mask:0xf
	v_mov_b32_dpp v120, v48 row_shr:1 row_mask:0xf bank_mask:0xf
	v_mov_b32_dpp v124, v144 row_shr:1 row_mask:0xf bank_mask:0xf
	v_mov_b32_dpp v121, v49 row_shr:1 row_mask:0xf bank_mask:0xf
	v_mov_b32_dpp v125, v145 row_shr:1 row_mask:0xf bank_mask:0xf
	v_pk_fma_f32 v[142:143], v[154:155], v[142:143], v[158:159]
	v_pk_fma_f32 v[144:145], v[156:157], v[144:145], v[160:161]
	v_pk_fma_f32 v[142:143], v[150:151], v[46:47], v[142:143]
	v_pk_fma_f32 v[144:145], v[152:153], v[48:49], v[144:145]
	v_pk_fma_f32 v[142:143], v[146:147], v[50:51], v[142:143]
	v_pk_fma_f32 v[144:145], v[148:149], v[52:53], v[144:145]
	v_pk_fma_f32 v[46:47], v[154:155], v[46:47], v[158:159]
	v_pk_fma_f32 v[48:49], v[156:157], v[48:49], v[160:161]
	v_pk_fma_f32 v[46:47], v[150:151], v[50:51], v[46:47]
	v_pk_fma_f32 v[48:49], v[152:153], v[52:53], v[48:49]
	v_pk_fma_f32 v[46:47], v[146:147], v[62:63], v[46:47]
	v_pk_fma_f32 v[48:49], v[148:149], v[64:65], v[48:49]
	v_pk_fma_f32 v[50:51], v[154:155], v[50:51], v[158:159]
	v_pk_fma_f32 v[52:53], v[156:157], v[52:53], v[160:161]
	v_pk_fma_f32 v[50:51], v[150:151], v[62:63], v[50:51]
	v_pk_fma_f32 v[52:53], v[152:153], v[64:65], v[52:53]
	v_pk_fma_f32 v[50:51], v[146:147], v[122:123], v[50:51]
	v_pk_fma_f32 v[52:53], v[148:149], v[124:125], v[52:53]
	v_pk_fma_f32 v[62:63], v[154:155], v[62:63], v[158:159]
	v_pk_fma_f32 v[64:65], v[156:157], v[64:65], v[160:161]
	v_pk_fma_f32 v[62:63], v[150:151], v[122:123], v[62:63]
	v_pk_fma_f32 v[64:65], v[152:153], v[124:125], v[64:65]
	v_pk_fma_f32 v[62:63], v[146:147], v[118:119], v[62:63]
	v_pk_fma_f32 v[64:65], v[148:149], v[120:121], v[64:65]
	s_cmp_lg_u32 s54, 0
	s_cbranch_scc1 .Lnepib_np2
	v_cmp_eq_u32_e32 vcc, 0, v224
	s_and_saveexec_b64 s[8:9], vcc
	s_add_u32 s52, s88, 0x2d00000
	s_addc_u32 s53, s89, 0
	global_store_dwordx4 v228, v[62:65], s[52:53] offset:0
	global_store_dwordx4 v230, v[50:53], s[52:53] offset:0
	s_or_b64 exec, exec, s[8:9]
	s_nop 1
.Lnepib_np2:
	v_pk_mul_f32 v[30:31], v[62:63], s[100:101]
	v_pk_mul_f32 v[32:33], v[64:65], s[100:101]
	v_pk_mul_f32 v[54:55], v[50:51], s[100:101]
	v_pk_mul_f32 v[56:57], v[52:53], s[100:101]
	v_exp_f32_e32 v30, v30
	v_exp_f32_e32 v31, v31
	v_exp_f32_e32 v32, v32
	v_exp_f32_e32 v33, v33
	v_exp_f32_e32 v54, v54
	v_exp_f32_e32 v55, v55
	v_exp_f32_e32 v56, v56
	v_exp_f32_e32 v57, v57
	v_pk_add_f32 v[30:31], v[30:31], s[98:99]
	v_pk_add_f32 v[32:33], v[32:33], s[98:99]
	v_pk_add_f32 v[54:55], v[54:55], s[98:99]
	v_pk_add_f32 v[56:57], v[56:57], s[98:99]
	v_rcp_f32_e32 v30, v30
	v_rcp_f32_e32 v31, v31
	v_rcp_f32_e32 v32, v32
	v_rcp_f32_e32 v33, v33
	v_rcp_f32_e32 v54, v54
	v_rcp_f32_e32 v55, v55
	v_rcp_f32_e32 v56, v56
	v_rcp_f32_e32 v57, v57
	v_pk_mul_f32 v[62:63], v[62:63], v[134:135]
	v_pk_mul_f32 v[64:65], v[64:65], v[136:137]
	v_pk_mul_f32 v[50:51], v[50:51], v[130:131]
	v_pk_mul_f32 v[52:53], v[52:53], v[132:133]
	v_pk_mul_f32 v[62:63], v[62:63], v[30:31]
	v_pk_mul_f32 v[64:65], v[64:65], v[32:33]
	v_pk_mul_f32 v[50:51], v[50:51], v[54:55]
	v_pk_mul_f32 v[52:53], v[52:53], v[56:57]
	v_pk_mul_f32 v[30:31], v[46:47], s[100:101]
	v_pk_mul_f32 v[32:33], v[48:49], s[100:101]
	v_pk_mul_f32 v[54:55], v[142:143], s[100:101]
	v_pk_mul_f32 v[56:57], v[144:145], s[100:101]
	v_exp_f32_e32 v30, v30
	v_exp_f32_e32 v31, v31
	v_exp_f32_e32 v32, v32
	v_exp_f32_e32 v33, v33
	v_exp_f32_e32 v54, v54
	v_exp_f32_e32 v55, v55
	v_exp_f32_e32 v56, v56
	v_exp_f32_e32 v57, v57
	v_pk_add_f32 v[30:31], v[30:31], s[98:99]
	v_pk_add_f32 v[32:33], v[32:33], s[98:99]
	v_pk_add_f32 v[54:55], v[54:55], s[98:99]
	v_pk_add_f32 v[56:57], v[56:57], s[98:99]
	v_rcp_f32_e32 v30, v30
	v_rcp_f32_e32 v31, v31
	v_rcp_f32_e32 v32, v32
	v_rcp_f32_e32 v33, v33
	v_rcp_f32_e32 v54, v54
	v_rcp_f32_e32 v55, v55
	v_rcp_f32_e32 v56, v56
	v_rcp_f32_e32 v57, v57
	v_pk_mul_f32 v[46:47], v[46:47], v[78:79]
	v_pk_mul_f32 v[48:49], v[48:49], v[80:81]
	v_pk_mul_f32 v[142:143], v[142:143], v[138:139]
	v_pk_mul_f32 v[144:145], v[144:145], v[140:141]
	v_pk_mul_f32 v[46:47], v[46:47], v[30:31]
	v_pk_mul_f32 v[48:49], v[48:49], v[32:33]
	v_pk_mul_f32 v[142:143], v[142:143], v[54:55]
	v_pk_mul_f32 v[144:145], v[144:145], v[56:57]
	s_waitcnt lgkmcnt(0)
	ds_read_b128 v[196:199], v226 offset:528
	ds_read_b128 v[200:203], v226 offset:1552
	ds_read_b128 v[204:207], v226 offset:2576
	ds_read_b128 v[208:211], v226 offset:3600
	s_cmp_eq_u32 s54, 0
	s_cbranch_scc1 .Lnepib_z4
	v_cmp_eq_u32_e32 vcc, 0, v224
	s_and_saveexec_b64 s[8:9], vcc
	ds_read_b128 v[118:121], v227 offset:528
	ds_read_b128 v[122:125], v227 offset:1552
	s_or_b64 exec, exec, s[8:9]
	s_branch .Lnepib_j4

.Lnepib_j4:
	v_mov_b32_dpp v162, v86 row_shr:1 row_mask:0xf bank_mask:0xf
	v_mov_b32_dpp v166, v114 row_shr:1 row_mask:0xf bank_mask:0xf
	v_mov_b32_dpp v163, v87 row_shr:1 row_mask:0xf bank_mask:0xf
	v_mov_b32_dpp v167, v115 row_shr:1 row_mask:0xf bank_mask:0xf
	v_mov_b32_dpp v164, v88 row_shr:1 row_mask:0xf bank_mask:0xf
	v_mov_b32_dpp v168, v116 row_shr:1 row_mask:0xf bank_mask:0xf
	v_mov_b32_dpp v165, v89 row_shr:1 row_mask:0xf bank_mask:0xf
	v_mov_b32_dpp v169, v117 row_shr:1 row_mask:0xf bank_mask:0xf
	v_pk_fma_f32 v[114:115], v[154:155], v[114:115], v[158:159]
	v_pk_fma_f32 v[116:117], v[156:157], v[116:117], v[160:161]
	v_pk_fma_f32 v[114:115], v[150:151], v[86:87], v[114:115]
	v_pk_fma_f32 v[116:117], v[152:153], v[88:89], v[116:117]
	v_pk_fma_f32 v[114:115], v[146:147], v[90:91], v[114:115]
	v_pk_fma_f32 v[116:117], v[148:149], v[92:93], v[116:117]
	v_pk_fma_f32 v[86:87], v[154:155], v[86:87], v[158:159]
	v_pk_fma_f32 v[88:89], v[156:157], v[88:89], v[160:161]
	v_pk_fma_f32 v[86:87], v[150:151], v[90:91], v[86:87]
	v_pk_fma_f32 v[88:89], v[152:153], v[92:93], v[88:89]
	v_pk_fma_f32 v[86:87], v[146:147], v[94:95], v[86:87]
	v_pk_fma_f32 v[88:89], v[148:149], v[96:97], v[88:89]
	v_pk_fma_f32 v[90:91], v[154:155], v[90:91], v[158:159]
	v_pk_fma_f32 v[92:93], v[156:157], v[92:93], v[160:161]
	v_pk_fma_f32 v[90:91], v[150:151], v[94:95], v[90:91]
	v_pk_fma_f32 v[92:93], v[152:153], v[96:97], v[92:93]
	v_pk_fma_f32 v[90:91], v[146:147], v[166:167], v[90:91]
	v_pk_fma_f32 v[92:93], v[148:149], v[168:169], v[92:93]
	v_pk_fma_f32 v[94:95], v[154:155], v[94:95], v[158:159]
	v_pk_fma_f32 v[96:97], v[156:157], v[96:97], v[160:161]
	v_pk_fma_f32 v[94:95], v[150:151], v[166:167], v[94:95]
	v_pk_fma_f32 v[96:97], v[152:153], v[168:169], v[96:97]
	v_pk_fma_f32 v[94:95], v[146:147], v[162:163], v[94:95]
	v_pk_fma_f32 v[96:97], v[148:149], v[164:165], v[96:97]
	v_pk_mul_f32 v[30:31], v[94:95], s[100:101]
	v_pk_mul_f32 v[32:33], v[96:97], s[100:101]
	v_pk_mul_f32 v[54:55], v[90:91], s[100:101]
	v_pk_mul_f32 v[56:57], v[92:93], s[100:101]
	v_exp_f32_e32 v30, v30
	v_exp_f32_e32 v31, v31
	v_exp_f32_e32 v32, v32
	v_exp_f32_e32 v33, v33
	v_exp_f32_e32 v54, v54
	v_exp_f32_e32 v55, v55
	v_exp_f32_e32 v56, v56
	v_exp_f32_e32 v57, v57
	v_pk_add_f32 v[30:31], v[30:31], s[98:99]
	v_pk_add_f32 v[32:33], v[32:33], s[98:99]
	v_pk_add_f32 v[54:55], v[54:55], s[98:99]
	v_pk_add_f32 v[56:57], v[56:57], s[98:99]
	v_rcp_f32_e32 v30, v30
	v_rcp_f32_e32 v31, v31
	v_rcp_f32_e32 v32, v32
	v_rcp_f32_e32 v33, v33
	v_rcp_f32_e32 v54, v54
	v_rcp_f32_e32 v55, v55
	v_rcp_f32_e32 v56, v56
	v_rcp_f32_e32 v57, v57
	v_pk_mul_f32 v[94:95], v[94:95], v[110:111]
	v_pk_mul_f32 v[96:97], v[96:97], v[112:113]
	v_pk_mul_f32 v[90:91], v[90:91], v[106:107]
	v_pk_mul_f32 v[92:93], v[92:93], v[108:109]
	v_pk_mul_f32 v[94:95], v[94:95], v[30:31]
	v_pk_mul_f32 v[96:97], v[96:97], v[32:33]
	v_pk_mul_f32 v[90:91], v[90:91], v[54:55]
	v_pk_mul_f32 v[92:93], v[92:93], v[56:57]
	v_pk_mul_f32 v[30:31], v[86:87], s[100:101]
	v_pk_mul_f32 v[32:33], v[88:89], s[100:101]
	v_pk_mul_f32 v[54:55], v[114:115], s[100:101]
	v_pk_mul_f32 v[56:57], v[116:117], s[100:101]
	v_exp_f32_e32 v30, v30
	v_exp_f32_e32 v31, v31
	v_exp_f32_e32 v32, v32
	v_exp_f32_e32 v33, v33
	v_exp_f32_e32 v54, v54
	v_exp_f32_e32 v55, v55
	v_exp_f32_e32 v56, v56
	v_exp_f32_e32 v57, v57
	v_pk_add_f32 v[30:31], v[30:31], s[98:99]
	v_pk_add_f32 v[32:33], v[32:33], s[98:99]
	v_pk_add_f32 v[54:55], v[54:55], s[98:99]
	v_pk_add_f32 v[56:57], v[56:57], s[98:99]
	v_rcp_f32_e32 v30, v30
	v_rcp_f32_e32 v31, v31
	v_rcp_f32_e32 v32, v32
	v_rcp_f32_e32 v33, v33
	v_rcp_f32_e32 v54, v54
	v_rcp_f32_e32 v55, v55
	v_rcp_f32_e32 v56, v56
	v_rcp_f32_e32 v57, v57
	v_pk_mul_f32 v[86:87], v[86:87], v[102:103]
	v_pk_mul_f32 v[88:89], v[88:89], v[104:105]
	v_pk_mul_f32 v[114:115], v[114:115], v[126:127]
	v_pk_mul_f32 v[116:117], v[116:117], v[128:129]
	v_pk_mul_f32 v[86:87], v[86:87], v[30:31]
	v_pk_mul_f32 v[88:89], v[88:89], v[32:33]
	v_pk_mul_f32 v[114:115], v[114:115], v[54:55]
	v_pk_mul_f32 v[116:117], v[116:117], v[56:57]
	s_waitcnt lgkmcnt(0)
	v_cmp_eq_u32_e32 vcc, 0, v224
	s_and_saveexec_b64 s[8:9], vcc
	ds_read_b128 v[162:165], v227 offset:4624
	ds_read_b128 v[166:169], v227 offset:5648
	s_or_b64 exec, exec, s[8:9]
	v_mov_b32_dpp v118, v66 row_shr:1 row_mask:0xf bank_mask:0xf
	v_mov_b32_dpp v122, v98 row_shr:1 row_mask:0xf bank_mask:0xf
	v_mov_b32_dpp v119, v67 row_shr:1 row_mask:0xf bank_mask:0xf
	v_mov_b32_dpp v123, v99 row_shr:1 row_mask:0xf bank_mask:0xf
	v_mov_b32_dpp v120, v68 row_shr:1 row_mask:0xf bank_mask:0xf
	v_mov_b32_dpp v124, v100 row_shr:1 row_mask:0xf bank_mask:0xf
	v_mov_b32_dpp v121, v69 row_shr:1 row_mask:0xf bank_mask:0xf
	v_mov_b32_dpp v125, v101 row_shr:1 row_mask:0xf bank_mask:0xf
	v_pk_fma_f32 v[98:99], v[204:205], v[98:99], v[208:209]
	v_pk_fma_f32 v[100:101], v[206:207], v[100:101], v[210:211]
	v_pk_fma_f32 v[98:99], v[200:201], v[66:67], v[98:99]
	v_pk_fma_f32 v[100:101], v[202:203], v[68:69], v[100:101]
	v_pk_fma_f32 v[98:99], v[196:197], v[70:71], v[98:99]
	v_pk_fma_f32 v[100:101], v[198:199], v[72:73], v[100:101]
	v_pk_fma_f32 v[66:67], v[204:205], v[66:67], v[208:209]
	v_pk_fma_f32 v[68:69], v[206:207], v[68:69], v[210:211]
	v_pk_fma_f32 v[66:67], v[200:201], v[70:71], v[66:67]
	v_pk_fma_f32 v[68:69], v[202:203], v[72:73], v[68:69]
	v_pk_fma_f32 v[66:67], v[196:197], v[74:75], v[66:67]
	v_pk_fma_f32 v[68:69], v[198:199], v[76:77], v[68:69]
	v_pk_fma_f32 v[70:71], v[204:205], v[70:71], v[208:209]
	v_pk_fma_f32 v[72:73], v[206:207], v[72:73], v[210:211]
	v_pk_fma_f32 v[70:71], v[200:201], v[74:75], v[70:71]
	v_pk_fma_f32 v[72:73], v[202:203], v[76:77], v[72:73]
	v_pk_fma_f32 v[70:71], v[196:197], v[122:123], v[70:71]
	v_pk_fma_f32 v[72:73], v[198:199], v[124:125], v[72:73]
	v_pk_fma_f32 v[74:75], v[204:205], v[74:75], v[208:209]
	v_pk_fma_f32 v[76:77], v[206:207], v[76:77], v[210:211]
	v_pk_fma_f32 v[74:75], v[200:201], v[122:123], v[74:75]
	v_pk_fma_f32 v[76:77], v[202:203], v[124:125], v[76:77]
	v_pk_fma_f32 v[74:75], v[196:197], v[118:119], v[74:75]
	v_pk_fma_f32 v[76:77], v[198:199], v[120:121], v[76:77]
	s_cmp_lg_u32 s54, 0
	s_cbranch_scc1 .Lnepib_np4
	v_cmp_eq_u32_e32 vcc, 0, v224
	s_and_saveexec_b64 s[8:9], vcc
	s_add_u32 s52, s88, 0x2d00000
	s_addc_u32 s53, s89, 0
	global_store_dwordx4 v229, v[74:77], s[52:53] offset:16
	global_store_dwordx4 v231, v[70:73], s[52:53] offset:16
	s_or_b64 exec, exec, s[8:9]
	s_nop 1
.Lnepib_np4:
	s_waitcnt lgkmcnt(0)
	ds_read_b128 v[146:149], v226 offset:16
	ds_read_b128 v[150:153], v226 offset:1040
	ds_read_b128 v[154:157], v226 offset:2064
	ds_read_b128 v[158:161], v226 offset:3088
	s_cmp_eq_u32 s54, 0
	s_cbranch_scc1 .Lnepib_z6
	v_cmp_eq_u32_e32 vcc, 0, v224
	s_and_saveexec_b64 s[8:9], vcc
	ds_read_b128 v[118:121], v227 offset:16
	ds_read_b128 v[122:125], v227 offset:1040
	s_or_b64 exec, exec, s[8:9]
	s_branch .Lnepib_j6

.Lnepib_j6:
	v_mov_b32_dpp v162, v14 row_shr:1 row_mask:0xf bank_mask:0xf
	v_mov_b32_dpp v166, v58 row_shr:1 row_mask:0xf bank_mask:0xf
	v_mov_b32_dpp v163, v15 row_shr:1 row_mask:0xf bank_mask:0xf
	v_mov_b32_dpp v167, v59 row_shr:1 row_mask:0xf bank_mask:0xf
	v_mov_b32_dpp v164, v16 row_shr:1 row_mask:0xf bank_mask:0xf
	v_mov_b32_dpp v168, v60 row_shr:1 row_mask:0xf bank_mask:0xf
	v_mov_b32_dpp v165, v17 row_shr:1 row_mask:0xf bank_mask:0xf
	v_mov_b32_dpp v169, v61 row_shr:1 row_mask:0xf bank_mask:0xf
	v_pk_fma_f32 v[58:59], v[204:205], v[58:59], v[208:209]
	v_pk_fma_f32 v[60:61], v[206:207], v[60:61], v[210:211]
	v_pk_fma_f32 v[58:59], v[200:201], v[14:15], v[58:59]
	v_pk_fma_f32 v[60:61], v[202:203], v[16:17], v[60:61]
	v_pk_fma_f32 v[58:59], v[196:197], v[18:19], v[58:59]
	v_pk_fma_f32 v[60:61], v[198:199], v[20:21], v[60:61]
	v_pk_fma_f32 v[14:15], v[204:205], v[14:15], v[208:209]
	v_pk_fma_f32 v[16:17], v[206:207], v[16:17], v[210:211]
	v_pk_fma_f32 v[14:15], v[200:201], v[18:19], v[14:15]
	v_pk_fma_f32 v[16:17], v[202:203], v[20:21], v[16:17]
	v_pk_fma_f32 v[14:15], v[196:197], v[22:23], v[14:15]
	v_pk_fma_f32 v[16:17], v[198:199], v[24:25], v[16:17]
	v_pk_fma_f32 v[18:19], v[204:205], v[18:19], v[208:209]
	v_pk_fma_f32 v[20:21], v[206:207], v[20:21], v[210:211]
	v_pk_fma_f32 v[18:19], v[200:201], v[22:23], v[18:19]
	v_pk_fma_f32 v[20:21], v[202:203], v[24:25], v[20:21]
	v_pk_fma_f32 v[18:19], v[196:197], v[166:167], v[18:19]
	v_pk_fma_f32 v[20:21], v[198:199], v[168:169], v[20:21]
	v_pk_fma_f32 v[22:23], v[204:205], v[22:23], v[208:209]
	v_pk_fma_f32 v[24:25], v[206:207], v[24:25], v[210:211]
	v_pk_fma_f32 v[22:23], v[200:201], v[166:167], v[22:23]
	v_pk_fma_f32 v[24:25], v[202:203], v[168:169], v[24:25]
	v_pk_fma_f32 v[22:23], v[196:197], v[162:163], v[22:23]
	v_pk_fma_f32 v[24:25], v[198:199], v[164:165], v[24:25]
	s_waitcnt lgkmcnt(0)
	v_cmp_eq_u32_e32 vcc, 0, v224
	s_and_saveexec_b64 s[8:9], vcc
	ds_read_b128 v[162:165], v227 offset:4112
	ds_read_b128 v[166:169], v227 offset:5136
	s_or_b64 exec, exec, s[8:9]
	v_mov_b32_dpp v118, v34 row_shr:1 row_mask:0xf bank_mask:0xf
	v_mov_b32_dpp v122, v82 row_shr:1 row_mask:0xf bank_mask:0xf
	v_mov_b32_dpp v119, v35 row_shr:1 row_mask:0xf bank_mask:0xf
	v_mov_b32_dpp v123, v83 row_shr:1 row_mask:0xf bank_mask:0xf
	v_mov_b32_dpp v120, v36 row_shr:1 row_mask:0xf bank_mask:0xf
	v_mov_b32_dpp v124, v84 row_shr:1 row_mask:0xf bank_mask:0xf
	v_mov_b32_dpp v121, v37 row_shr:1 row_mask:0xf bank_mask:0xf
	v_mov_b32_dpp v125, v85 row_shr:1 row_mask:0xf bank_mask:0xf
	v_pk_fma_f32 v[82:83], v[154:155], v[82:83], v[158:159]
	v_pk_fma_f32 v[84:85], v[156:157], v[84:85], v[160:161]
	v_pk_fma_f32 v[82:83], v[150:151], v[34:35], v[82:83]
	v_pk_fma_f32 v[84:85], v[152:153], v[36:37], v[84:85]
	v_pk_fma_f32 v[82:83], v[146:147], v[38:39], v[82:83]
	v_pk_fma_f32 v[84:85], v[148:149], v[40:41], v[84:85]
	v_pk_fma_f32 v[34:35], v[154:155], v[34:35], v[158:159]
	v_pk_fma_f32 v[36:37], v[156:157], v[36:37], v[160:161]
	v_pk_fma_f32 v[34:35], v[150:151], v[38:39], v[34:35]
	v_pk_fma_f32 v[36:37], v[152:153], v[40:41], v[36:37]
	v_pk_fma_f32 v[34:35], v[146:147], v[42:43], v[34:35]
	v_pk_fma_f32 v[36:37], v[148:149], v[44:45], v[36:37]
	v_pk_fma_f32 v[38:39], v[154:155], v[38:39], v[158:159]
	v_pk_fma_f32 v[40:41], v[156:157], v[40:41], v[160:161]
	v_pk_fma_f32 v[38:39], v[150:151], v[42:43], v[38:39]
	v_pk_fma_f32 v[40:41], v[152:153], v[44:45], v[40:41]
	v_pk_fma_f32 v[38:39], v[146:147], v[122:123], v[38:39]
	v_pk_fma_f32 v[40:41], v[148:149], v[124:125], v[40:41]
	v_pk_fma_f32 v[42:43], v[154:155], v[42:43], v[158:159]
	v_pk_fma_f32 v[44:45], v[156:157], v[44:45], v[160:161]
	v_pk_fma_f32 v[42:43], v[150:151], v[122:123], v[42:43]
	v_pk_fma_f32 v[44:45], v[152:153], v[124:125], v[44:45]
	v_pk_fma_f32 v[42:43], v[146:147], v[118:119], v[42:43]
	v_pk_fma_f32 v[44:45], v[148:149], v[120:121], v[44:45]
	s_cmp_lg_u32 s54, 0
	s_cbranch_scc1 .Lnepib_np6
	v_cmp_eq_u32_e32 vcc, 0, v224
	s_and_saveexec_b64 s[8:9], vcc
	s_add_u32 s52, s88, 0x2d00000
	s_addc_u32 s53, s89, 0
	global_store_dwordx4 v228, v[42:45], s[52:53] offset:16
	global_store_dwordx4 v230, v[38:41], s[52:53] offset:16
	s_or_b64 exec, exec, s[8:9]
	s_nop 1
